# scan: log decay produced in log2 units (B1 scale folded), 18 multiplies per thread-step removed
# baseline (speedup 1.0000x reference)
; __device__ __forceinline__ int crow(int r, int hi) { return (r & 3) + 8 * (r >> 2) + 4 * hi; }
; #define OPAQUE_TID(name) int name = MK_TID; asm volatile("" : "+v"(name))
; __device__ __forceinline__ void scan_unit(const int unit, const Args& a, unsigned char* lds, const int mk_wid) {
;     ...
;         __syncthreads();
;         { OPAQUE_TID(t_); const int lane = t_ & 63, r32 = lane & 31, hi = lane >> 5; const int tt = wid >> 2, ct = wid & 3;
;           const bf16x8 af = *(const bf16x8*)(lds + L_LR + (tt * 32 + r32) * 32 + hi * 16);
;           const f32x16 z = __builtin_amdgcn_mfma_f32_32x32x16_bf16(af, upf, f32x16{}, 0, 0, 0);
;           float* lw = las + (tt * 32 + 4 * hi) * 128 + ct * 32 + r32;
; #pragma unroll
;           for (int r = 0; r < 16; ++r) { const float zz = z[r] + biasc;
;               lw[crow(r, 0) * 128] = (fminf(zz, 0.f) - __builtin_amdgcn_logf(1.f + __builtin_amdgcn_exp2f(-1.4426950408889634f * fabsf(zz))) * 0.6931471805599453f) * (1.f / 16.f); } }
.Lscan_noflush:
	s_waitcnt lgkmcnt(0)
	s_barrier
	v_mbcnt_lo_u32_b32 v64, -1, 0
	v_mbcnt_hi_u32_b32 v64, -1, v64
	s_nop 0
	v_add_u32_e32 v64, s72, v64
	s_nop 0
	v_and_b32_e32 v68, 31, v64
	v_bfe_u32 v69, v64, 5, 1
	v_lshlrev_b32_e32 v64, 5, v68
	v_lshlrev_b32_e32 v65, 4, v69
	v_add3_u32 v64, s44, v64, v65
	ds_read_b128 v[64:67], v64
	v_lshlrev_b32_e32 v69, 11, v69
	v_lshlrev_b32_e32 v68, 2, v68
	v_add3_u32 v80, s45, v69, v68
	s_waitcnt lgkmcnt(0)
	v_mfma_f32_32x32x16_bf16 v[64:79], v[64:67], v[108:111], 0
	s_nop 11
	v_add_f32_e32 v64, v156, v64
	v_add_f32_e32 v65, v156, v65
	v_mul_f32_e64 v81, |v64|, s54
	v_mul_f32_e64 v82, |v65|, s54
	v_exp_f32_e32 v81, v81
	v_exp_f32_e32 v82, v82
	v_add_f32_e32 v66, v156, v66
	v_min_f32_e32 v64, 0, v64
	v_add_f32_e32 v81, 1.0, v81
	v_add_f32_e32 v82, 1.0, v82
	v_log_f32_e32 v81, v81
	v_log_f32_e32 v82, v82
	v_min_f32_e32 v65, 0, v65
	v_mul_f32_e64 v83, |v66|, s54
	v_fmac_f32_e32 v64, 0xbf317218, v81
	v_fmac_f32_e32 v65, 0xbf317218, v82
	v_add_f32_e32 v67, v156, v67
	v_exp_f32_e32 v83, v83
	v_mul_f32_e32 v64, 0x3db8aa3b, v64
	v_mul_f32_e32 v65, 0x3db8aa3b, v65
	ds_write2st64_b32 v80, v64, v65 offset1:2
	v_mul_f32_e64 v64, |v67|, s54
	v_exp_f32_e32 v64, v64
	v_add_f32_e32 v65, 1.0, v83
	v_log_f32_e32 v65, v65
	v_min_f32_e32 v66, 0, v66
	v_add_f32_e32 v64, 1.0, v64
	v_log_f32_e32 v64, v64
	v_fmac_f32_e32 v66, 0xbf317218, v65
	v_mul_f32_e32 v65, 0x3db8aa3b, v66
	v_min_f32_e32 v66, 0, v67
	v_fmac_f32_e32 v66, 0xbf317218, v64
	v_mul_f32_e32 v64, 0x3db8aa3b, v66
	ds_write2st64_b32 v80, v65, v64 offset0:4 offset1:6
	v_add_f32_e32 v64, v156, v68
	v_mul_f32_e64 v65, |v64|, s54
	v_add_f32_e32 v66, v156, v69
	v_exp_f32_e32 v65, v65
	v_mul_f32_e64 v67, |v66|, s54
	v_exp_f32_e32 v67, v67
	v_min_f32_e32 v64, 0, v64
	v_add_f32_e32 v65, 1.0, v65
	v_log_f32_e32 v65, v65
	v_add_f32_e32 v67, 1.0, v67
	v_log_f32_e32 v67, v67
	v_fmac_f32_e32 v64, 0xbf317218, v65
	v_min_f32_e32 v65, 0, v66
	v_fmac_f32_e32 v65, 0xbf317218, v67
	v_mul_f32_e32 v64, 0x3db8aa3b, v64
	v_mul_f32_e32 v65, 0x3db8aa3b, v65
	ds_write2st64_b32 v80, v64, v65 offset0:16 offset1:18
	v_add_f32_e32 v64, v156, v70
	v_mul_f32_e64 v65, |v64|, s54
	v_add_f32_e32 v66, v156, v71
	v_exp_f32_e32 v65, v65
	v_mul_f32_e64 v67, |v66|, s54
	v_exp_f32_e32 v67, v67
	v_min_f32_e32 v64, 0, v64
	v_add_f32_e32 v65, 1.0, v65
	v_log_f32_e32 v65, v65
	v_add_f32_e32 v67, 1.0, v67
	v_log_f32_e32 v67, v67
	v_fmac_f32_e32 v64, 0xbf317218, v65
	v_min_f32_e32 v65, 0, v66
	v_fmac_f32_e32 v65, 0xbf317218, v67
	v_mul_f32_e32 v64, 0x3db8aa3b, v64
	v_mul_f32_e32 v65, 0x3db8aa3b, v65
	ds_write2st64_b32 v80, v64, v65 offset0:20 offset1:22
	v_add_f32_e32 v64, v156, v72
	v_mul_f32_e64 v65, |v64|, s54
	v_add_f32_e32 v66, v156, v73
	v_exp_f32_e32 v65, v65
	v_mul_f32_e64 v67, |v66|, s54
	v_exp_f32_e32 v67, v67
	v_min_f32_e32 v64, 0, v64
	v_add_f32_e32 v65, 1.0, v65
	v_log_f32_e32 v65, v65
	v_add_f32_e32 v67, 1.0, v67
	v_log_f32_e32 v67, v67
	v_fmac_f32_e32 v64, 0xbf317218, v65
	v_min_f32_e32 v65, 0, v66
	v_fmac_f32_e32 v65, 0xbf317218, v67
	v_mul_f32_e32 v64, 0x3db8aa3b, v64
	v_mul_f32_e32 v65, 0x3db8aa3b, v65
	ds_write2st64_b32 v80, v64, v65 offset0:32 offset1:34
	v_add_f32_e32 v64, v156, v74
	v_mul_f32_e64 v65, |v64|, s54
	v_add_f32_e32 v66, v156, v75
	v_exp_f32_e32 v65, v65
	v_mul_f32_e64 v67, |v66|, s54
	v_exp_f32_e32 v67, v67
	v_min_f32_e32 v64, 0, v64
	v_add_f32_e32 v65, 1.0, v65
	v_log_f32_e32 v65, v65
	v_add_f32_e32 v67, 1.0, v67
	v_log_f32_e32 v67, v67
	v_fmac_f32_e32 v64, 0xbf317218, v65
	v_min_f32_e32 v65, 0, v66
	v_fmac_f32_e32 v65, 0xbf317218, v67
	v_mul_f32_e32 v64, 0x3db8aa3b, v64
	v_mul_f32_e32 v65, 0x3db8aa3b, v65
	ds_write2st64_b32 v80, v64, v65 offset0:36 offset1:38
	v_add_f32_e32 v64, v156, v76
	v_mul_f32_e64 v65, |v64|, s54
	v_add_f32_e32 v66, v156, v77
	v_exp_f32_e32 v65, v65
	v_mul_f32_e64 v67, |v66|, s54
	v_exp_f32_e32 v67, v67
	v_min_f32_e32 v64, 0, v64
	v_add_f32_e32 v65, 1.0, v65
	v_log_f32_e32 v65, v65
	v_add_f32_e32 v67, 1.0, v67
	v_log_f32_e32 v67, v67
	v_fmac_f32_e32 v64, 0xbf317218, v65
	v_min_f32_e32 v65, 0, v66
	v_fmac_f32_e32 v65, 0xbf317218, v67
	v_mul_f32_e32 v64, 0x3db8aa3b, v64
	v_mul_f32_e32 v65, 0x3db8aa3b, v65
	ds_write2st64_b32 v80, v64, v65 offset0:48 offset1:50
	v_add_f32_e32 v64, v156, v78
	v_mul_f32_e64 v65, |v64|, s54
	v_add_f32_e32 v66, v156, v79
	v_exp_f32_e32 v65, v65
	v_mul_f32_e64 v67, |v66|, s54
	v_exp_f32_e32 v67, v67
	v_min_f32_e32 v64, 0, v64
	v_add_f32_e32 v65, 1.0, v65
	v_log_f32_e32 v65, v65
	v_add_f32_e32 v67, 1.0, v67
	v_log_f32_e32 v67, v67
	v_fmac_f32_e32 v64, 0xbf317218, v65
	v_min_f32_e32 v65, 0, v66
	v_fmac_f32_e32 v65, 0xbf317218, v67
	v_mul_f32_e32 v64, 0x3db8aa3b, v64
	v_mul_f32_e32 v65, 0x3db8aa3b, v65
	ds_write2st64_b32 v80, v64, v65 offset0:52 offset1:54
	s_waitcnt lgkmcnt(0)
	s_barrier
; __device__ __forceinline__ int v_st(int k, int c) { const int kk = (k & ~0xC) | ((k & 4) << 1) | ((k & 8) >> 1); return ((kk >> 3) * 4 + (c >> 5)) * 512 + ((kk & 7) * 32 + (c & 31)) * 2; }
; __device__ __forceinline__ float bf2f(short s) { return __uint_as_float(((unsigned)(unsigned short)s) << 16); }
; __device__ __forceinline__ float bf2f(u16 u) { return __uint_as_float((unsigned)u << 16); }
; __device__ __forceinline__ u16 f2bf(float f) { return (u16)(pk2(f, 0.f) & 0xffffu); }
; #define OPAQUE_TID(name) int name = MK_TID; asm volatile("" : "+v"(name))
; __device__ __forceinline__ void scan_unit(const int unit, const Args& a, unsigned char* lds, const int mk_wid) {
;     ...
;         { OPAQUE_TID(t_); const int c = t_ & 127, g = t_ >> 7;
;           float bl[16]; float run = 0.f;
;           { const float* lp = las + (g * 16) * 128 + c;
; #pragma unroll
;             for (int ii = 0; ii < 16; ++ii) { run += lp[ii * 128]; bl[ii] = run; } }
;           gs[g * 128 + c] = run;
;           __syncthreads();
;           const float g0 = gs[c], g1 = gs[128 + c], g2 = gs[256 + c], g3 = gs[384 + c];
;           const float off = (g > 0 ? g0 : 0.f) + (g > 1 ? g1 : 0.f) + (g > 2 ? g2 : 0.f);
;           const float btot = (g0 + g1) + (g2 + g3);
;           const float dlc = __builtin_amdgcn_exp2f(btot * 1.4426950408889634f);
;           if (g == 0) dl[c] = dlc;
;           u16* qcol = qe + (g * 16) * QP + c; u16* kcol = ke + (g * 16) * QP + c; unsigned char* kdb = lds + L_KD + v_st(g * 16, c);
; #pragma unroll
;           for (int ii = 0; ii < 16; ++ii) { const float bb = bl[ii] + off;
;               const float qf = bf2f(qcol[ii * QP]), kf = bf2f(kcol[ii * QP]);
;               const float e = __builtin_amdgcn_exp2f(bb * 1.4426950408889634f), ker = kf * __builtin_amdgcn_rcpf(e);
;               qcol[ii * QP] = f2bf(qf * (0.088388347648318440f * e));
;               kcol[ii * QP] = f2bf(ker);
;               *(u16*)(kdb + v_st(ii, 0)) = f2bf(ker * dlc); } }
	v_mbcnt_lo_u32_b32 v64, -1, 0
	v_mbcnt_hi_u32_b32 v64, -1, v64
	s_lshl_b32 s96, s70, 12
	s_add_i32 s96, s96, s9
	v_lshl_add_u32 v65, v64, 3, s96
	ds_read_b64 v[170:171], v65
	ds_read_b64 v[172:173], v65 offset:512
	ds_read_b64 v[174:175], v65 offset:1024
	ds_read_b64 v[176:177], v65 offset:1536
	ds_read_b64 v[178:179], v65 offset:2048
	ds_read_b64 v[180:181], v65 offset:2560
	ds_read_b64 v[182:183], v65 offset:3072
	ds_read_b64 v[184:185], v65 offset:3584
	s_cmp_gt_u32 s70, 0
	s_cselect_b32 s97, 1.0, 0
	v_mov_b32_e32 v238, s97
	s_cmp_gt_u32 s70, 1
	s_cselect_b32 s97, 1.0, 0
	v_mov_b32_e32 v239, s97
	s_cmp_gt_u32 s70, 2
	s_cselect_b32 s97, 1.0, 0
	v_mov_b32_e32 v240, s97
	s_cmp_gt_u32 s70, 3
	s_cselect_b32 s97, 1.0, 0
	v_mov_b32_e32 v241, s97
	s_cmp_gt_u32 s70, 4
	s_cselect_b32 s97, 1.0, 0
	v_mov_b32_e32 v242, s97
	s_cmp_gt_u32 s70, 5
	s_cselect_b32 s97, 1.0, 0
	v_mov_b32_e32 v243, s97
	s_cmp_gt_u32 s70, 6
	s_cselect_b32 s97, 1.0, 0
	v_mov_b32_e32 v244, s97
	s_lshl_b32 s98, s70, 9
	s_add_i32 s98, s98, 0x20000
	v_lshl_add_u32 v66, v64, 3, s98
	v_lshlrev_b32_e32 v67, 3, v64
	v_add_u32_e32 v67, 0x20000, v67
	s_mul_i32 s99, s70, 0x880
	v_lshl_add_u32 v68, v64, 2, s99
	v_and_b32_e32 v94, 2, v64
	v_lshlrev_b32_e32 v94, 1, v94
	v_and_b32_e32 v95, 4, v64
	v_lshrrev_b32_e32 v95, 1, v95
	v_and_b32_e32 v70, 0xfffffff9, v64
	v_or3_b32 v94, v94, v95, v70
	v_lshl_add_u32 v94, v94, 2, s99
	s_lshr_b32 s98, s70, 1
	s_lshl_b32 s98, s98, 12
	s_and_b32 s99, s70, 1
	s_lshl_b32 s99, s99, 8
	s_add_i32 s98, s98, s99
	v_lshrrev_b32_e32 v69, 4, v64
	v_lshlrev_b32_e32 v69, 9, v69
	v_and_b32_e32 v70, 15, v64
	v_lshl_add_u32 v69, v70, 2, v69
	v_add_u32_e32 v69, s98, v69
	s_waitcnt lgkmcnt(7)
	v_add_f32_e32 v170, 0, v170
	v_add_f32_e32 v171, 0, v171
	s_waitcnt lgkmcnt(6)
	v_add_f32_e32 v172, v170, v172
	v_add_f32_e32 v173, v171, v173
	s_waitcnt lgkmcnt(5)
	v_add_f32_e32 v174, v172, v174
	v_add_f32_e32 v175, v173, v175
	s_waitcnt lgkmcnt(4)
	v_add_f32_e32 v176, v174, v176
	v_add_f32_e32 v177, v175, v177
	s_waitcnt lgkmcnt(3)
	v_add_f32_e32 v178, v176, v178
	v_add_f32_e32 v179, v177, v179
	s_waitcnt lgkmcnt(2)
	v_add_f32_e32 v180, v178, v180
	v_add_f32_e32 v181, v179, v181
	s_waitcnt lgkmcnt(1)
	v_add_f32_e32 v182, v180, v182
	v_add_f32_e32 v183, v181, v183
	s_waitcnt lgkmcnt(0)
	v_add_f32_e32 v184, v182, v184
	v_add_f32_e32 v185, v183, v185
	ds_write_b64 v66, v[184:185]
	s_waitcnt lgkmcnt(0)
	s_barrier
	ds_read_b64 v[72:73], v67
	ds_read_b64 v[74:75], v67 offset:512
	ds_read_b64 v[76:77], v67 offset:1024
	ds_read_b64 v[78:79], v67 offset:1536
	ds_read_b64 v[80:81], v67 offset:2048
	ds_read_b64 v[82:83], v67 offset:2560
	ds_read_b64 v[84:85], v67 offset:3072
	ds_read_b64 v[86:87], v67 offset:3584
	ds_read_b32 v202, v68
	ds_read_b32 v210, v68 offset:17408
	ds_read_b32 v203, v68 offset:272
	ds_read_b32 v211, v68 offset:17680
	ds_read_b32 v204, v68 offset:544
	ds_read_b32 v212, v68 offset:17952
	s_waitcnt lgkmcnt(6)
	ds_read_b32 v205, v68 offset:816
	ds_read_b32 v213, v68 offset:18224
	ds_read_b32 v206, v68 offset:1088
	ds_read_b32 v214, v68 offset:18496
	ds_read_b32 v207, v68 offset:1360
	ds_read_b32 v215, v68 offset:18768
	ds_read_b32 v208, v68 offset:1632
	ds_read_b32 v216, v68 offset:19040
	v_mul_f32_e32 v88, v238, v72
	v_mul_f32_e32 v89, v238, v73
	v_fmac_f32_e32 v88, v239, v74
	v_fmac_f32_e32 v89, v239, v75
	v_fmac_f32_e32 v88, v240, v76
	v_fmac_f32_e32 v89, v240, v77
	v_fmac_f32_e32 v88, v241, v78
	v_fmac_f32_e32 v89, v241, v79
	v_fmac_f32_e32 v88, v242, v80
	v_fmac_f32_e32 v89, v242, v81
	v_fmac_f32_e32 v88, v243, v82
	v_fmac_f32_e32 v89, v243, v83
	v_fmac_f32_e32 v88, v244, v84
	v_fmac_f32_e32 v89, v244, v85
	v_add_f32_e32 v90, v72, v74
	v_add_f32_e32 v91, v73, v75
	v_add_f32_e32 v90, v90, v76
	v_add_f32_e32 v91, v91, v77
	v_add_f32_e32 v90, v90, v78
	v_add_f32_e32 v91, v91, v79
	v_add_f32_e32 v90, v90, v80
	v_add_f32_e32 v91, v91, v81
	v_add_f32_e32 v90, v90, v82
	v_add_f32_e32 v91, v91, v83
	v_add_f32_e32 v90, v90, v84
	v_add_f32_e32 v91, v91, v85
	v_add_f32_e32 v90, v90, v86
	v_add_f32_e32 v91, v91, v87
	v_mov_b32_e32 v92, v90
	v_mov_b32_e32 v93, v91
	v_exp_f32_e32 v92, v92
	v_exp_f32_e32 v93, v93
	v_add_f32_e32 v170, v170, v88
	v_add_f32_e32 v171, v171, v89
	v_add_f32_e32 v172, v172, v88
	v_add_f32_e32 v173, v173, v89
	v_add_f32_e32 v174, v174, v88
	v_add_f32_e32 v175, v175, v89
	v_add_f32_e32 v176, v176, v88
	v_add_f32_e32 v177, v177, v89
	v_add_f32_e32 v178, v178, v88
	v_add_f32_e32 v179, v179, v89
	v_add_f32_e32 v180, v180, v88
	v_add_f32_e32 v181, v181, v89
	v_add_f32_e32 v182, v182, v88
	v_add_f32_e32 v183, v183, v89
	v_add_f32_e32 v184, v184, v88
	v_add_f32_e32 v185, v185, v89
	v_exp_f32_e32 v170, v170
	v_exp_f32_e32 v171, v171
	v_exp_f32_e32 v172, v172
	v_exp_f32_e32 v173, v173
	v_exp_f32_e32 v174, v174
	v_exp_f32_e32 v175, v175
	v_exp_f32_e32 v176, v176
	v_exp_f32_e32 v177, v177
	v_exp_f32_e32 v178, v178
	v_exp_f32_e32 v179, v179
	v_exp_f32_e32 v180, v180
	v_exp_f32_e32 v181, v181
	v_exp_f32_e32 v182, v182
	v_exp_f32_e32 v183, v183
	v_exp_f32_e32 v184, v184
	v_exp_f32_e32 v185, v185
	v_rcp_f32_e32 v186, v170
	v_rcp_f32_e32 v187, v171
	v_rcp_f32_e32 v188, v172
	v_rcp_f32_e32 v189, v173
	v_rcp_f32_e32 v190, v174
	v_rcp_f32_e32 v191, v175
	v_rcp_f32_e32 v192, v176
	v_rcp_f32_e32 v193, v177
	v_rcp_f32_e32 v194, v178
	v_rcp_f32_e32 v195, v179
	v_rcp_f32_e32 v196, v180
	v_rcp_f32_e32 v197, v181
	v_rcp_f32_e32 v198, v182
	v_rcp_f32_e32 v199, v183
	v_rcp_f32_e32 v200, v184
	v_rcp_f32_e32 v201, v185
	v_mul_f32_e32 v170, 0x3db504f3, v170
	v_mul_f32_e32 v171, 0x3db504f3, v171
	v_mul_f32_e32 v172, 0x3db504f3, v172
	v_mul_f32_e32 v173, 0x3db504f3, v173
	v_mul_f32_e32 v174, 0x3db504f3, v174
	v_mul_f32_e32 v175, 0x3db504f3, v175
	v_mul_f32_e32 v176, 0x3db504f3, v176
	v_mul_f32_e32 v177, 0x3db504f3, v177
	v_mul_f32_e32 v178, 0x3db504f3, v178
	v_mul_f32_e32 v179, 0x3db504f3, v179
	v_mul_f32_e32 v180, 0x3db504f3, v180
	v_mul_f32_e32 v181, 0x3db504f3, v181
	v_mul_f32_e32 v182, 0x3db504f3, v182
	v_mul_f32_e32 v183, 0x3db504f3, v183
	v_mul_f32_e32 v184, 0x3db504f3, v184
	v_mul_f32_e32 v185, 0x3db504f3, v185
	s_cmp_lg_u32 s70, 0
	s_cbranch_scc1 .Lscan_c2_nodl
	v_lshlrev_b32_e32 v70, 3, v64
	v_add_u32_e32 v70, 0x1fc00, v70
	ds_write_b64 v70, v[92:93]
